# v6 stack plus 64-byte alignment of both GEMM main-loop heads
# baseline (speedup 1.0000x reference)
.LBB0_217:
	s_add_u32 s24, s46, 0x100
	s_addc_u32 s25, s47, 0
	s_ashr_i32 s23, s22, 31
	s_lshl_b64 s[42:43], s[22:23], 21
	s_add_u32 s44, s92, s42
	s_addc_u32 s45, s93, s43
	s_and_b64 s[42:43], s[40:41], exec
	s_cselect_b32 s23, s45, s19
	s_cselect_b32 vcc_lo, s44, s18
	s_ashr_i32 s21, s20, 31
	s_lshl_b64 s[42:43], s[20:21], 21
	s_add_u32 s42, s52, s42
	s_addc_u32 s43, s69, s43
	s_and_b64 s[48:49], s[40:41], exec
	s_cselect_b32 s21, s43, s47
	s_cselect_b32 vcc_hi, s42, s46
	s_add_u32 s46, s18, 0x100080
	s_addc_u32 s47, s19, 0
	v_lshl_add_u64 v[142:143], s[46:47], 0, v[138:139]
	v_lshl_add_u64 v[144:145], s[46:47], 0, v[140:141]
	s_mov_b32 s13, -2
	s_mov_b64 s[46:47], 0
	.p2align	6

.LBB0_258:
	s_ashr_i32 s19, s18, 31
	v_cmp_lt_i64_e32 vcc, s[20:21], v[214:215]
	s_lshl_b64 s[20:21], s[18:19], 20
	s_add_u32 s20, s94, s20
	s_addc_u32 s21, s95, s21
	s_and_b64 s[22:23], vcc, exec
	s_cselect_b32 s19, s21, s41
	s_cselect_b32 s24, s20, s40
	s_ashr_i32 s17, s16, 31
	s_lshl_b64 s[22:23], s[16:17], 20
	s_add_u32 s22, s49, s22
	s_addc_u32 s23, s52, s23
	s_and_b64 s[44:45], vcc, exec
	s_cselect_b32 s17, s23, s43
	s_cselect_b32 s25, s22, s42
	s_add_u32 s40, s40, 0x80080
	s_addc_u32 s41, s41, 0
	s_add_u32 s33, s42, 0x100
	v_mov_b32_e32 v2, 0
	s_addc_u32 s80, s43, 0
	s_mov_b32 s81, -2
	v_mov_b32_e32 v3, v2
	v_mov_b32_e32 v4, v2
	v_mov_b32_e32 v5, v2
	v_mov_b32_e32 v6, v2
	v_mov_b32_e32 v7, v2
	v_mov_b32_e32 v8, v2
	v_mov_b32_e32 v9, v2
	v_mov_b32_e32 v18, v2
	v_mov_b32_e32 v19, v2
	v_mov_b32_e32 v20, v2
	v_mov_b32_e32 v21, v2
	v_mov_b32_e32 v22, v2
	v_mov_b32_e32 v23, v2
	v_mov_b32_e32 v24, v2
	v_mov_b32_e32 v25, v2
	v_mov_b32_e32 v34, v2
	v_mov_b32_e32 v35, v2
	v_mov_b32_e32 v36, v2
	v_mov_b32_e32 v37, v2
	v_mov_b32_e32 v38, v2
	v_mov_b32_e32 v39, v2
	v_mov_b32_e32 v40, v2
	v_mov_b32_e32 v41, v2
	v_mov_b32_e32 v50, v2
	v_mov_b32_e32 v51, v2
	v_mov_b32_e32 v52, v2
	v_mov_b32_e32 v53, v2
	v_mov_b32_e32 v54, v2
	v_mov_b32_e32 v55, v2
	v_mov_b32_e32 v56, v2
	v_mov_b32_e32 v57, v2
	v_mov_b32_e32 v10, v2
	v_mov_b32_e32 v11, v2
	v_mov_b32_e32 v12, v2
	v_mov_b32_e32 v13, v2
	v_mov_b32_e32 v14, v2
	v_mov_b32_e32 v15, v2
	v_mov_b32_e32 v16, v2
	v_mov_b32_e32 v17, v2
	v_mov_b32_e32 v26, v2
	v_mov_b32_e32 v27, v2
	v_mov_b32_e32 v28, v2
	v_mov_b32_e32 v29, v2
	v_mov_b32_e32 v30, v2
	v_mov_b32_e32 v31, v2
	v_mov_b32_e32 v32, v2
	v_mov_b32_e32 v33, v2
	v_mov_b32_e32 v42, v2
	v_mov_b32_e32 v43, v2
	v_mov_b32_e32 v44, v2
	v_mov_b32_e32 v45, v2
	v_mov_b32_e32 v46, v2
	v_mov_b32_e32 v47, v2
	v_mov_b32_e32 v48, v2
	v_mov_b32_e32 v49, v2
	v_mov_b32_e32 v58, v2
	v_mov_b32_e32 v59, v2
	v_mov_b32_e32 v60, v2
	v_mov_b32_e32 v61, v2
	v_mov_b32_e32 v62, v2
	v_mov_b32_e32 v63, v2
	v_mov_b32_e32 v64, v2
	v_mov_b32_e32 v65, v2
	v_mov_b32_e32 v66, v2
	v_mov_b32_e32 v67, v2
	v_mov_b32_e32 v68, v2
	v_mov_b32_e32 v69, v2
	v_mov_b32_e32 v70, v2
	v_mov_b32_e32 v71, v2
	v_mov_b32_e32 v72, v2
	v_mov_b32_e32 v73, v2
	v_mov_b32_e32 v82, v2
	v_mov_b32_e32 v83, v2
	v_mov_b32_e32 v84, v2
	v_mov_b32_e32 v85, v2
	v_mov_b32_e32 v86, v2
	v_mov_b32_e32 v87, v2
	v_mov_b32_e32 v88, v2
	v_mov_b32_e32 v89, v2
	v_mov_b32_e32 v98, v2
	v_mov_b32_e32 v99, v2
	v_mov_b32_e32 v100, v2
	v_mov_b32_e32 v101, v2
	v_mov_b32_e32 v102, v2
	v_mov_b32_e32 v103, v2
	v_mov_b32_e32 v104, v2
	v_mov_b32_e32 v105, v2
	v_mov_b32_e32 v114, v2
	v_mov_b32_e32 v115, v2
	v_mov_b32_e32 v116, v2
	v_mov_b32_e32 v117, v2
	v_mov_b32_e32 v118, v2
	v_mov_b32_e32 v119, v2
	v_mov_b32_e32 v120, v2
	v_mov_b32_e32 v121, v2
	v_mov_b32_e32 v74, v2
	v_mov_b32_e32 v75, v2
	v_mov_b32_e32 v76, v2
	v_mov_b32_e32 v77, v2
	v_mov_b32_e32 v78, v2
	v_mov_b32_e32 v79, v2
	v_mov_b32_e32 v80, v2
	v_mov_b32_e32 v81, v2
	v_mov_b32_e32 v90, v2
	v_mov_b32_e32 v91, v2
	v_mov_b32_e32 v92, v2
	v_mov_b32_e32 v93, v2
	v_mov_b32_e32 v94, v2
	v_mov_b32_e32 v95, v2
	v_mov_b32_e32 v96, v2
	v_mov_b32_e32 v97, v2
	v_mov_b32_e32 v106, v2
	v_mov_b32_e32 v107, v2
	v_mov_b32_e32 v108, v2
	v_mov_b32_e32 v109, v2
	v_mov_b32_e32 v110, v2
	v_mov_b32_e32 v111, v2
	v_mov_b32_e32 v112, v2
	v_mov_b32_e32 v113, v2
	v_mov_b32_e32 v122, v2
	v_mov_b32_e32 v123, v2
	v_mov_b32_e32 v124, v2
	v_mov_b32_e32 v125, v2
	v_mov_b32_e32 v126, v2
	v_mov_b32_e32 v127, v2
	v_mov_b32_e32 v128, v2
	v_mov_b32_e32 v129, v2
	.p2align	6
